# r1 + in-proj RMSNorm gain vectors loaded once per unit instead of 32 serialized loads
# speedup vs baseline: 1.0058x; 1.0058x over previous
;     __device__ __forceinline__ void operator()(const f32x4 (&acc)[2][2][4][2], const Unit& u, int wr, int wc, int fr_, int fq_) const {
;     ...
;                 if (gain) {
;                     float ss = 0.f;
; #pragma unroll
;                     for (int bj = 0; bj < 2; ++bj)
; #pragma unroll
;                         for (int n = 0; n < 2; ++n) ss += (v[bj][n][0] * v[bj][n][0] + v[bj][n][1] * v[bj][n][1]) + (v[bj][n][2] * v[bj][n][2] + v[bj][n][3] * v[bj][n][3]);
;                     ss += __shfl_xor(ss, 16); ss += __shfl_xor(ss, 32);
;                     const float rinv = __builtin_amdgcn_rsqf(ss * (1.0f / 64.0f) + RMS_EPS);
; #pragma unroll
;                     for (int bj = 0; bj < 2; ++bj)
; #pragma unroll
;                         for (int n = 0; n < 2; ++n) v[bj][n] = v[bj][n] * rinv * *(const f32x4*)(gain + 32 * bj + 16 * n + 4 * fq);
;                 }
.LBB0_208:
	v_lshlrev_b32_e32 v140, 2, v155
	s_cmp_lg_u64 s[76:77], 0
	v_ashrrev_i32_e32 v141, 31, v140
	s_cselect_b64 s[16:17], -1, 0
	s_cmp_eq_u64 s[76:77], 0
	v_lshl_add_u64 v[138:139], v[140:141], 2, s[76:77]
	s_cbranch_scc1 .LBB0_210
	global_load_dwordx4 v[178:181], v[138:139], off
	global_load_dwordx4 v[182:185], v[138:139], off offset:64
	global_load_dwordx4 v[186:189], v[138:139], off offset:128
	global_load_dwordx4 v[190:193], v[138:139], off offset:192
	v_pk_mul_f32 v[142:143], v[128:129], v[128:129]
	v_pk_mul_f32 v[144:145], v[126:127], v[126:127]
	v_mul_f32_e32 v0, v122, v122
	v_pk_mov_b32 v[146:147], v[144:145], v[142:143] op_sel:[1,0]
	v_mov_b32_e32 v145, v143
	v_pk_add_f32 v[142:143], v[146:147], v[144:145]
	v_pk_mul_f32 v[144:145], v[120:121], v[120:121]
	v_pk_mul_f32 v[146:147], v[118:119], v[118:119]
	v_pk_add_f32 v[142:143], v[142:143], v[142:143] op_sel:[0,1] op_sel_hi:[1,0]
	v_pk_mov_b32 v[148:149], v[146:147], v[144:145] op_sel:[1,0]
	v_mov_b32_e32 v147, v145
	v_pk_add_f32 v[144:145], v[148:149], v[146:147]
	v_mul_f32_e32 v146, v123, v123
	v_pk_add_f32 v[144:145], v[144:145], v[144:145] op_sel:[0,1] op_sel_hi:[1,0]
	v_mov_b32_e32 v143, v0
	v_mov_b32_e32 v145, v146
	v_mul_f32_e32 v0, v115, v115
	v_mul_f32_e32 v147, v124, v124
	v_pk_add_f32 v[142:143], v[142:143], v[144:145]
	v_pk_fma_f32 v[144:145], v[114:115], v[114:115], v[0:1] op_sel_hi:[1,1,0]
	v_mul_f32_e32 v0, v117, v117
	v_mul_f32_e32 v148, v125, v125
	v_mov_b32_e32 v145, v147
	v_pk_fma_f32 v[146:147], v[116:117], v[116:117], v[0:1] op_sel_hi:[1,1,0]
	s_nop 0
	v_mov_b32_e32 v147, v148
	v_pk_add_f32 v[144:145], v[144:145], v[146:147]
	s_nop 0
	v_pk_add_f32 v[142:143], v[142:143], v[144:145]
	s_nop 0
	v_add_f32_e32 v0, v142, v143
	v_and_b32_e32 v143, 64, v242
	v_xor_b32_e32 v142, 16, v242
	v_add_u32_e32 v143, 64, v143
	v_cmp_lt_i32_e32 vcc, v142, v143
	s_nop 1
	v_cndmask_b32_e32 v142, v242, v142, vcc
	v_lshlrev_b32_e32 v142, 2, v142
	ds_bpermute_b32 v142, v142, v0
	s_waitcnt lgkmcnt(0)
	v_add_f32_e32 v0, v0, v142
	v_xor_b32_e32 v142, 32, v242
	v_cmp_lt_i32_e32 vcc, v142, v143
	s_nop 1
	v_cndmask_b32_e32 v142, v242, v142, vcc
	v_lshlrev_b32_e32 v142, 2, v142
	ds_bpermute_b32 v142, v142, v0
	s_waitcnt lgkmcnt(0)
	v_add_f32_e32 v0, v0, v142
	v_fmamk_f32 v0, v0, 0x3c800000, v241
	v_rsq_f32_e32 v0, v0
	s_nop 0
	v_pk_mul_f32 v[142:143], v[126:127], v[0:1] op_sel_hi:[1,0]
	v_pk_mul_f32 v[144:145], v[128:129], v[0:1] op_sel_hi:[1,0]
	s_waitcnt vmcnt(0)
	v_mov_b64_e32 v[126:127], v[178:179]
	v_mov_b64_e32 v[128:129], v[180:181]
	v_pk_mul_f32 v[122:123], v[122:123], v[0:1] op_sel_hi:[1,0]
	v_pk_mul_f32 v[124:125], v[124:125], v[0:1] op_sel_hi:[1,0]
	v_pk_mul_f32 v[128:129], v[128:129], v[144:145]
	v_pk_mul_f32 v[126:127], v[126:127], v[142:143]
	v_pk_mul_f32 v[142:143], v[118:119], v[0:1] op_sel_hi:[1,0]
	v_pk_mul_f32 v[144:145], v[120:121], v[0:1] op_sel_hi:[1,0]
	v_mov_b64_e32 v[118:119], v[182:183]
	v_mov_b64_e32 v[120:121], v[184:185]
	v_pk_mul_f32 v[120:121], v[120:121], v[144:145]
	v_pk_mul_f32 v[118:119], v[118:119], v[142:143]
	v_pk_mul_f32 v[142:143], v[114:115], v[0:1] op_sel_hi:[1,0]
	v_pk_mul_f32 v[144:145], v[116:117], v[0:1] op_sel_hi:[1,0]
	v_mov_b64_e32 v[114:115], v[186:187]
	v_mov_b64_e32 v[116:117], v[188:189]
	v_pk_mul_f32 v[116:117], v[116:117], v[144:145]
	v_pk_mul_f32 v[114:115], v[114:115], v[142:143]
	v_mov_b64_e32 v[142:143], v[190:191]
	v_mov_b64_e32 v[144:145], v[192:193]
	v_pk_mul_f32 v[124:125], v[144:145], v[124:125]
	v_pk_mul_f32 v[122:123], v[142:143], v[122:123]

;     __device__ __forceinline__ void operator()(const f32x4 (&acc)[2][2][4][2], const Unit& u, int wr, int wc, int fr_, int fq_) const {
;     ...
;                 if (gain) {
;                     float ss = 0.f;
; #pragma unroll
;                     for (int bj = 0; bj < 2; ++bj)
; #pragma unroll
;                         for (int n = 0; n < 2; ++n) ss += (v[bj][n][0] * v[bj][n][0] + v[bj][n][1] * v[bj][n][1]) + (v[bj][n][2] * v[bj][n][2] + v[bj][n][3] * v[bj][n][3]);
;                     ss += __shfl_xor(ss, 16); ss += __shfl_xor(ss, 32);
;                     const float rinv = __builtin_amdgcn_rsqf(ss * (1.0f / 64.0f) + RMS_EPS);
; #pragma unroll
;                     for (int bj = 0; bj < 2; ++bj)
; #pragma unroll
;                         for (int n = 0; n < 2; ++n) v[bj][n] = v[bj][n] * rinv * *(const f32x4*)(gain + 32 * bj + 16 * n + 4 * fq);
;                 }
.LBB0_233:
	v_cndmask_b32_e64 v0, 0, 1, s[16:17]
	v_cmp_ne_u32_e64 s[14:15], 1, v0
	s_andn2_b64 vcc, exec, s[16:17]
	s_cbranch_vccnz .LBB0_235
	v_pk_mul_f32 v[114:115], v[112:113], v[112:113]
	v_pk_mul_f32 v[116:117], v[110:111], v[110:111]
	v_mul_f32_e32 v0, v106, v106
	v_pk_mov_b32 v[118:119], v[116:117], v[114:115] op_sel:[1,0]
	v_mov_b32_e32 v117, v115
	v_pk_add_f32 v[114:115], v[118:119], v[116:117]
	v_pk_mul_f32 v[116:117], v[104:105], v[104:105]
	v_pk_mul_f32 v[118:119], v[102:103], v[102:103]
	v_pk_add_f32 v[114:115], v[114:115], v[114:115] op_sel:[0,1] op_sel_hi:[1,0]
	v_pk_mov_b32 v[120:121], v[118:119], v[116:117] op_sel:[1,0]
	v_mov_b32_e32 v119, v117
	v_pk_add_f32 v[116:117], v[120:121], v[118:119]
	v_mul_f32_e32 v118, v107, v107
	v_pk_add_f32 v[116:117], v[116:117], v[116:117] op_sel:[0,1] op_sel_hi:[1,0]
	v_mov_b32_e32 v115, v0
	v_mov_b32_e32 v117, v118
	v_mul_f32_e32 v0, v99, v99
	v_mul_f32_e32 v119, v108, v108
	v_pk_add_f32 v[114:115], v[114:115], v[116:117]
	v_pk_fma_f32 v[116:117], v[98:99], v[98:99], v[0:1] op_sel_hi:[1,1,0]
	v_mul_f32_e32 v0, v101, v101
	v_mul_f32_e32 v120, v109, v109
	v_mov_b32_e32 v117, v119
	v_pk_fma_f32 v[118:119], v[100:101], v[100:101], v[0:1] op_sel_hi:[1,1,0]
	s_nop 0
	v_mov_b32_e32 v119, v120
	v_pk_add_f32 v[116:117], v[116:117], v[118:119]
	s_nop 0
	v_pk_add_f32 v[114:115], v[114:115], v[116:117]
	s_nop 0
	v_add_f32_e32 v0, v114, v115
	v_and_b32_e32 v115, 64, v242
	v_xor_b32_e32 v114, 16, v242
	v_add_u32_e32 v115, 64, v115
	v_cmp_lt_i32_e32 vcc, v114, v115
	s_nop 1
	v_cndmask_b32_e32 v114, v242, v114, vcc
	v_lshlrev_b32_e32 v114, 2, v114
	ds_bpermute_b32 v114, v114, v0
	s_waitcnt lgkmcnt(0)
	v_add_f32_e32 v0, v0, v114
	v_xor_b32_e32 v114, 32, v242
	v_cmp_lt_i32_e32 vcc, v114, v115
	s_nop 1
	v_cndmask_b32_e32 v114, v242, v114, vcc
	v_lshlrev_b32_e32 v114, 2, v114
	ds_bpermute_b32 v114, v114, v0
	s_waitcnt lgkmcnt(0)
	v_add_f32_e32 v0, v0, v114
	v_fmamk_f32 v0, v0, 0x3c800000, v241
	v_rsq_f32_e32 v0, v0
	s_nop 0
	v_pk_mul_f32 v[114:115], v[110:111], v[0:1] op_sel_hi:[1,0]
	v_pk_mul_f32 v[116:117], v[112:113], v[0:1] op_sel_hi:[1,0]
	v_mov_b64_e32 v[110:111], v[178:179]
	v_mov_b64_e32 v[112:113], v[180:181]
	v_pk_mul_f32 v[106:107], v[106:107], v[0:1] op_sel_hi:[1,0]
	v_pk_mul_f32 v[108:109], v[108:109], v[0:1] op_sel_hi:[1,0]
	v_pk_mul_f32 v[112:113], v[112:113], v[116:117]
	v_pk_mul_f32 v[110:111], v[110:111], v[114:115]
	v_pk_mul_f32 v[114:115], v[102:103], v[0:1] op_sel_hi:[1,0]
	v_pk_mul_f32 v[116:117], v[104:105], v[0:1] op_sel_hi:[1,0]
	v_mov_b64_e32 v[102:103], v[182:183]
	v_mov_b64_e32 v[104:105], v[184:185]
	v_pk_mul_f32 v[104:105], v[104:105], v[116:117]
	v_pk_mul_f32 v[102:103], v[102:103], v[114:115]
	v_pk_mul_f32 v[114:115], v[98:99], v[0:1] op_sel_hi:[1,0]
	v_pk_mul_f32 v[116:117], v[100:101], v[0:1] op_sel_hi:[1,0]
	v_mov_b64_e32 v[98:99], v[186:187]
	v_mov_b64_e32 v[100:101], v[188:189]
	v_pk_mul_f32 v[100:101], v[100:101], v[116:117]
	v_pk_mul_f32 v[98:99], v[98:99], v[114:115]
	v_mov_b64_e32 v[114:115], v[190:191]
	v_mov_b64_e32 v[116:117], v[192:193]
	v_pk_mul_f32 v[108:109], v[116:117], v[108:109]
	v_pk_mul_f32 v[106:107], v[114:115], v[106:107]

;     __device__ __forceinline__ void operator()(const f32x4 (&acc)[2][2][4][2], const Unit& u, int wr, int wc, int fr_, int fq_) const {
;     ...
;                 if (gain) {
;                     float ss = 0.f;
; #pragma unroll
;                     for (int bj = 0; bj < 2; ++bj)
; #pragma unroll
;                         for (int n = 0; n < 2; ++n) ss += (v[bj][n][0] * v[bj][n][0] + v[bj][n][1] * v[bj][n][1]) + (v[bj][n][2] * v[bj][n][2] + v[bj][n][3] * v[bj][n][3]);
;                     ss += __shfl_xor(ss, 16); ss += __shfl_xor(ss, 32);
;                     const float rinv = __builtin_amdgcn_rsqf(ss * (1.0f / 64.0f) + RMS_EPS);
; #pragma unroll
;                     for (int bj = 0; bj < 2; ++bj)
; #pragma unroll
;                         for (int n = 0; n < 2; ++n) v[bj][n] = v[bj][n] * rinv * *(const f32x4*)(gain + 32 * bj + 16 * n + 4 * fq);
;                 }
.LBB0_258:
	s_and_b64 vcc, exec, s[14:15]
	s_cbranch_vccnz .LBB0_260
	v_pk_mul_f32 v[98:99], v[96:97], v[96:97]
	v_pk_mul_f32 v[100:101], v[94:95], v[94:95]
	v_mul_f32_e32 v0, v90, v90
	v_pk_mov_b32 v[102:103], v[100:101], v[98:99] op_sel:[1,0]
	v_mov_b32_e32 v101, v99
	v_pk_add_f32 v[98:99], v[102:103], v[100:101]
	v_pk_mul_f32 v[100:101], v[88:89], v[88:89]
	v_pk_mul_f32 v[102:103], v[86:87], v[86:87]
	v_pk_add_f32 v[98:99], v[98:99], v[98:99] op_sel:[0,1] op_sel_hi:[1,0]
	v_pk_mov_b32 v[104:105], v[102:103], v[100:101] op_sel:[1,0]
	v_mov_b32_e32 v103, v101
	v_pk_add_f32 v[100:101], v[104:105], v[102:103]
	v_mul_f32_e32 v102, v91, v91
	v_pk_add_f32 v[100:101], v[100:101], v[100:101] op_sel:[0,1] op_sel_hi:[1,0]
	v_mov_b32_e32 v99, v0
	v_mov_b32_e32 v101, v102
	v_mul_f32_e32 v0, v83, v83
	v_mul_f32_e32 v103, v92, v92
	v_pk_add_f32 v[98:99], v[98:99], v[100:101]
	v_pk_fma_f32 v[100:101], v[82:83], v[82:83], v[0:1] op_sel_hi:[1,1,0]
	v_mul_f32_e32 v0, v85, v85
	v_mul_f32_e32 v104, v93, v93
	v_mov_b32_e32 v101, v103
	v_pk_fma_f32 v[102:103], v[84:85], v[84:85], v[0:1] op_sel_hi:[1,1,0]
	s_nop 0
	v_mov_b32_e32 v103, v104
	v_pk_add_f32 v[100:101], v[100:101], v[102:103]
	s_nop 0
	v_pk_add_f32 v[98:99], v[98:99], v[100:101]
	s_nop 0
	v_add_f32_e32 v0, v98, v99
	v_and_b32_e32 v99, 64, v242
	v_xor_b32_e32 v98, 16, v242
	v_add_u32_e32 v99, 64, v99
	v_cmp_lt_i32_e32 vcc, v98, v99
	s_nop 1
	v_cndmask_b32_e32 v98, v242, v98, vcc
	v_lshlrev_b32_e32 v98, 2, v98
	ds_bpermute_b32 v98, v98, v0
	s_waitcnt lgkmcnt(0)
	v_add_f32_e32 v0, v0, v98
	v_xor_b32_e32 v98, 32, v242
	v_cmp_lt_i32_e32 vcc, v98, v99
	s_nop 1
	v_cndmask_b32_e32 v98, v242, v98, vcc
	v_lshlrev_b32_e32 v98, 2, v98
	ds_bpermute_b32 v98, v98, v0
	s_waitcnt lgkmcnt(0)
	v_add_f32_e32 v0, v0, v98
	v_fmamk_f32 v0, v0, 0x3c800000, v241
	v_rsq_f32_e32 v0, v0
	s_nop 0
	v_pk_mul_f32 v[98:99], v[94:95], v[0:1] op_sel_hi:[1,0]
	v_pk_mul_f32 v[100:101], v[96:97], v[0:1] op_sel_hi:[1,0]
	v_mov_b64_e32 v[94:95], v[178:179]
	v_mov_b64_e32 v[96:97], v[180:181]
	v_pk_mul_f32 v[90:91], v[90:91], v[0:1] op_sel_hi:[1,0]
	v_pk_mul_f32 v[92:93], v[92:93], v[0:1] op_sel_hi:[1,0]
	v_pk_mul_f32 v[96:97], v[96:97], v[100:101]
	v_pk_mul_f32 v[94:95], v[94:95], v[98:99]
	v_pk_mul_f32 v[98:99], v[86:87], v[0:1] op_sel_hi:[1,0]
	v_pk_mul_f32 v[100:101], v[88:89], v[0:1] op_sel_hi:[1,0]
	v_mov_b64_e32 v[86:87], v[182:183]
	v_mov_b64_e32 v[88:89], v[184:185]
	v_pk_mul_f32 v[88:89], v[88:89], v[100:101]
	v_pk_mul_f32 v[86:87], v[86:87], v[98:99]
	v_pk_mul_f32 v[98:99], v[82:83], v[0:1] op_sel_hi:[1,0]
	v_pk_mul_f32 v[100:101], v[84:85], v[0:1] op_sel_hi:[1,0]
	v_mov_b64_e32 v[82:83], v[186:187]
	v_mov_b64_e32 v[84:85], v[188:189]
	v_pk_mul_f32 v[84:85], v[84:85], v[100:101]
	v_pk_mul_f32 v[82:83], v[82:83], v[98:99]
	v_mov_b64_e32 v[98:99], v[190:191]
	v_mov_b64_e32 v[100:101], v[192:193]
	v_pk_mul_f32 v[92:93], v[100:101], v[92:93]
	v_pk_mul_f32 v[90:91], v[98:99], v[90:91]

;     __device__ __forceinline__ void operator()(const f32x4 (&acc)[2][2][4][2], const Unit& u, int wr, int wc, int fr_, int fq_) const {
;     ...
;                 if (gain) {
;                     float ss = 0.f;
; #pragma unroll
;                     for (int bj = 0; bj < 2; ++bj)
; #pragma unroll
;                         for (int n = 0; n < 2; ++n) ss += (v[bj][n][0] * v[bj][n][0] + v[bj][n][1] * v[bj][n][1]) + (v[bj][n][2] * v[bj][n][2] + v[bj][n][3] * v[bj][n][3]);
;                     ss += __shfl_xor(ss, 16); ss += __shfl_xor(ss, 32);
;                     const float rinv = __builtin_amdgcn_rsqf(ss * (1.0f / 64.0f) + RMS_EPS);
; #pragma unroll
;                     for (int bj = 0; bj < 2; ++bj)
; #pragma unroll
;                         for (int n = 0; n < 2; ++n) v[bj][n] = v[bj][n] * rinv * *(const f32x4*)(gain + 32 * bj + 16 * n + 4 * fq);
;                 }
.LBB0_282:
	s_and_b64 vcc, exec, s[14:15]
	s_cbranch_vccnz .LBB0_284
	v_pk_mul_f32 v[82:83], v[80:81], v[80:81]
	v_pk_mul_f32 v[84:85], v[78:79], v[78:79]
	v_mul_f32_e32 v0, v74, v74
	v_pk_mov_b32 v[86:87], v[84:85], v[82:83] op_sel:[1,0]
	v_mov_b32_e32 v85, v83
	v_pk_add_f32 v[82:83], v[86:87], v[84:85]
	v_pk_mul_f32 v[84:85], v[72:73], v[72:73]
	v_pk_mul_f32 v[86:87], v[70:71], v[70:71]
	v_pk_add_f32 v[82:83], v[82:83], v[82:83] op_sel:[0,1] op_sel_hi:[1,0]
	v_pk_mov_b32 v[88:89], v[86:87], v[84:85] op_sel:[1,0]
	v_mov_b32_e32 v87, v85
	v_pk_add_f32 v[84:85], v[88:89], v[86:87]
	v_mul_f32_e32 v86, v75, v75
	v_pk_add_f32 v[84:85], v[84:85], v[84:85] op_sel:[0,1] op_sel_hi:[1,0]
	v_mov_b32_e32 v83, v0
	v_mov_b32_e32 v85, v86
	v_mul_f32_e32 v0, v67, v67
	v_mul_f32_e32 v87, v76, v76
	v_pk_add_f32 v[82:83], v[82:83], v[84:85]
	v_pk_fma_f32 v[84:85], v[66:67], v[66:67], v[0:1] op_sel_hi:[1,1,0]
	v_mul_f32_e32 v0, v69, v69
	v_mul_f32_e32 v88, v77, v77
	v_mov_b32_e32 v85, v87
	v_pk_fma_f32 v[86:87], v[68:69], v[68:69], v[0:1] op_sel_hi:[1,1,0]
	s_nop 0
	v_mov_b32_e32 v87, v88
	v_pk_add_f32 v[84:85], v[84:85], v[86:87]
	s_nop 0
	v_pk_add_f32 v[82:83], v[82:83], v[84:85]
	s_nop 0
	v_add_f32_e32 v0, v82, v83
	v_and_b32_e32 v83, 64, v242
	v_xor_b32_e32 v82, 16, v242
	v_add_u32_e32 v83, 64, v83
	v_cmp_lt_i32_e32 vcc, v82, v83
	s_nop 1
	v_cndmask_b32_e32 v82, v242, v82, vcc
	v_lshlrev_b32_e32 v82, 2, v82
	ds_bpermute_b32 v82, v82, v0
	s_waitcnt lgkmcnt(0)
	v_add_f32_e32 v0, v0, v82
	v_xor_b32_e32 v82, 32, v242
	v_cmp_lt_i32_e32 vcc, v82, v83
	s_nop 1
	v_cndmask_b32_e32 v82, v242, v82, vcc
	v_lshlrev_b32_e32 v82, 2, v82
	ds_bpermute_b32 v82, v82, v0
	s_waitcnt lgkmcnt(0)
	v_add_f32_e32 v0, v0, v82
	v_fmamk_f32 v0, v0, 0x3c800000, v241
	v_rsq_f32_e32 v0, v0
	s_nop 0
	v_pk_mul_f32 v[82:83], v[78:79], v[0:1] op_sel_hi:[1,0]
	v_pk_mul_f32 v[84:85], v[80:81], v[0:1] op_sel_hi:[1,0]
	v_mov_b64_e32 v[78:79], v[178:179]
	v_mov_b64_e32 v[80:81], v[180:181]
	v_pk_mul_f32 v[74:75], v[74:75], v[0:1] op_sel_hi:[1,0]
	v_pk_mul_f32 v[76:77], v[76:77], v[0:1] op_sel_hi:[1,0]
	v_pk_mul_f32 v[80:81], v[80:81], v[84:85]
	v_pk_mul_f32 v[78:79], v[78:79], v[82:83]
	v_pk_mul_f32 v[82:83], v[70:71], v[0:1] op_sel_hi:[1,0]
	v_pk_mul_f32 v[84:85], v[72:73], v[0:1] op_sel_hi:[1,0]
	v_mov_b64_e32 v[70:71], v[182:183]
	v_mov_b64_e32 v[72:73], v[184:185]
	v_pk_mul_f32 v[72:73], v[72:73], v[84:85]
	v_pk_mul_f32 v[70:71], v[70:71], v[82:83]
	v_pk_mul_f32 v[82:83], v[66:67], v[0:1] op_sel_hi:[1,0]
	v_pk_mul_f32 v[84:85], v[68:69], v[0:1] op_sel_hi:[1,0]
	v_mov_b64_e32 v[66:67], v[186:187]
	v_mov_b64_e32 v[68:69], v[188:189]
	v_pk_mul_f32 v[68:69], v[68:69], v[84:85]
	v_pk_mul_f32 v[66:67], v[66:67], v[82:83]
	v_mov_b64_e32 v[82:83], v[190:191]
	v_mov_b64_e32 v[84:85], v[192:193]
	v_pk_mul_f32 v[76:77], v[84:85], v[76:77]
	v_pk_mul_f32 v[74:75], v[82:83], v[74:75]

;     __device__ __forceinline__ void operator()(const f32x4 (&acc)[2][2][4][2], const Unit& u, int wr, int wc, int fr_, int fq_) const {
;     ...
;                 if (gain) {
;                     float ss = 0.f;
; #pragma unroll
;                     for (int bj = 0; bj < 2; ++bj)
; #pragma unroll
;                         for (int n = 0; n < 2; ++n) ss += (v[bj][n][0] * v[bj][n][0] + v[bj][n][1] * v[bj][n][1]) + (v[bj][n][2] * v[bj][n][2] + v[bj][n][3] * v[bj][n][3]);
;                     ss += __shfl_xor(ss, 16); ss += __shfl_xor(ss, 32);
;                     const float rinv = __builtin_amdgcn_rsqf(ss * (1.0f / 64.0f) + RMS_EPS);
; #pragma unroll
;                     for (int bj = 0; bj < 2; ++bj)
; #pragma unroll
;                         for (int n = 0; n < 2; ++n) v[bj][n] = v[bj][n] * rinv * *(const f32x4*)(gain + 32 * bj + 16 * n + 4 * fq);
;                 }
.LBB0_306:
	s_and_b64 vcc, exec, s[14:15]
	s_cbranch_vccnz .LBB0_308
	v_pk_mul_f32 v[66:67], v[64:65], v[64:65]
	v_pk_mul_f32 v[68:69], v[62:63], v[62:63]
	v_mul_f32_e32 v0, v58, v58
	v_pk_mov_b32 v[70:71], v[68:69], v[66:67] op_sel:[1,0]
	v_mov_b32_e32 v69, v67
	v_pk_add_f32 v[66:67], v[70:71], v[68:69]
	v_pk_mul_f32 v[68:69], v[56:57], v[56:57]
	v_pk_mul_f32 v[70:71], v[54:55], v[54:55]
	v_pk_add_f32 v[66:67], v[66:67], v[66:67] op_sel:[0,1] op_sel_hi:[1,0]
	v_pk_mov_b32 v[72:73], v[70:71], v[68:69] op_sel:[1,0]
	v_mov_b32_e32 v71, v69
	v_pk_add_f32 v[68:69], v[72:73], v[70:71]
	v_mul_f32_e32 v70, v59, v59
	v_pk_add_f32 v[68:69], v[68:69], v[68:69] op_sel:[0,1] op_sel_hi:[1,0]
	v_mov_b32_e32 v67, v0
	v_mov_b32_e32 v69, v70
	v_mul_f32_e32 v0, v51, v51
	v_mul_f32_e32 v71, v60, v60
	v_pk_add_f32 v[66:67], v[66:67], v[68:69]
	v_pk_fma_f32 v[68:69], v[50:51], v[50:51], v[0:1] op_sel_hi:[1,1,0]
	v_mul_f32_e32 v0, v53, v53
	v_mul_f32_e32 v72, v61, v61
	v_mov_b32_e32 v69, v71
	v_pk_fma_f32 v[70:71], v[52:53], v[52:53], v[0:1] op_sel_hi:[1,1,0]
	s_nop 0
	v_mov_b32_e32 v71, v72
	v_pk_add_f32 v[68:69], v[68:69], v[70:71]
	s_nop 0
	v_pk_add_f32 v[66:67], v[66:67], v[68:69]
	s_nop 0
	v_add_f32_e32 v0, v66, v67
	v_and_b32_e32 v67, 64, v242
	v_xor_b32_e32 v66, 16, v242
	v_add_u32_e32 v67, 64, v67
	v_cmp_lt_i32_e32 vcc, v66, v67
	s_nop 1
	v_cndmask_b32_e32 v66, v242, v66, vcc
	v_lshlrev_b32_e32 v66, 2, v66
	ds_bpermute_b32 v66, v66, v0
	s_waitcnt lgkmcnt(0)
	v_add_f32_e32 v0, v0, v66
	v_xor_b32_e32 v66, 32, v242
	v_cmp_lt_i32_e32 vcc, v66, v67
	s_nop 1
	v_cndmask_b32_e32 v66, v242, v66, vcc
	v_lshlrev_b32_e32 v66, 2, v66
	ds_bpermute_b32 v66, v66, v0
	s_waitcnt lgkmcnt(0)
	v_add_f32_e32 v0, v0, v66
	v_fmamk_f32 v0, v0, 0x3c800000, v241
	v_rsq_f32_e32 v0, v0
	s_nop 0
	v_pk_mul_f32 v[66:67], v[62:63], v[0:1] op_sel_hi:[1,0]
	v_pk_mul_f32 v[68:69], v[64:65], v[0:1] op_sel_hi:[1,0]
	v_mov_b64_e32 v[62:63], v[178:179]
	v_mov_b64_e32 v[64:65], v[180:181]
	v_pk_mul_f32 v[58:59], v[58:59], v[0:1] op_sel_hi:[1,0]
	v_pk_mul_f32 v[60:61], v[60:61], v[0:1] op_sel_hi:[1,0]
	v_pk_mul_f32 v[64:65], v[64:65], v[68:69]
	v_pk_mul_f32 v[62:63], v[62:63], v[66:67]
	v_pk_mul_f32 v[66:67], v[54:55], v[0:1] op_sel_hi:[1,0]
	v_pk_mul_f32 v[68:69], v[56:57], v[0:1] op_sel_hi:[1,0]
	v_mov_b64_e32 v[54:55], v[182:183]
	v_mov_b64_e32 v[56:57], v[184:185]
	v_pk_mul_f32 v[56:57], v[56:57], v[68:69]
	v_pk_mul_f32 v[54:55], v[54:55], v[66:67]
	v_pk_mul_f32 v[66:67], v[50:51], v[0:1] op_sel_hi:[1,0]
	v_pk_mul_f32 v[68:69], v[52:53], v[0:1] op_sel_hi:[1,0]
	v_mov_b64_e32 v[50:51], v[186:187]
	v_mov_b64_e32 v[52:53], v[188:189]
	v_pk_mul_f32 v[52:53], v[52:53], v[68:69]
	v_pk_mul_f32 v[50:51], v[50:51], v[66:67]
	v_mov_b64_e32 v[66:67], v[190:191]
	v_mov_b64_e32 v[68:69], v[192:193]
	v_pk_mul_f32 v[60:61], v[68:69], v[60:61]
	v_pk_mul_f32 v[58:59], v[66:67], v[58:59]

;     __device__ __forceinline__ void operator()(const f32x4 (&acc)[2][2][4][2], const Unit& u, int wr, int wc, int fr_, int fq_) const {
;     ...
;                 if (gain) {
;                     float ss = 0.f;
; #pragma unroll
;                     for (int bj = 0; bj < 2; ++bj)
; #pragma unroll
;                         for (int n = 0; n < 2; ++n) ss += (v[bj][n][0] * v[bj][n][0] + v[bj][n][1] * v[bj][n][1]) + (v[bj][n][2] * v[bj][n][2] + v[bj][n][3] * v[bj][n][3]);
;                     ss += __shfl_xor(ss, 16); ss += __shfl_xor(ss, 32);
;                     const float rinv = __builtin_amdgcn_rsqf(ss * (1.0f / 64.0f) + RMS_EPS);
; #pragma unroll
;                     for (int bj = 0; bj < 2; ++bj)
; #pragma unroll
;                         for (int n = 0; n < 2; ++n) v[bj][n] = v[bj][n] * rinv * *(const f32x4*)(gain + 32 * bj + 16 * n + 4 * fq);
;                 }
.LBB0_330:
	s_and_b64 vcc, exec, s[14:15]
	s_cbranch_vccnz .LBB0_332
	v_pk_mul_f32 v[50:51], v[48:49], v[48:49]
	v_pk_mul_f32 v[52:53], v[46:47], v[46:47]
	v_mul_f32_e32 v0, v42, v42
	v_pk_mov_b32 v[54:55], v[52:53], v[50:51] op_sel:[1,0]
	v_mov_b32_e32 v53, v51
	v_pk_add_f32 v[50:51], v[54:55], v[52:53]
	v_pk_mul_f32 v[52:53], v[40:41], v[40:41]
	v_pk_mul_f32 v[54:55], v[38:39], v[38:39]
	v_pk_add_f32 v[50:51], v[50:51], v[50:51] op_sel:[0,1] op_sel_hi:[1,0]
	v_pk_mov_b32 v[56:57], v[54:55], v[52:53] op_sel:[1,0]
	v_mov_b32_e32 v55, v53
	v_pk_add_f32 v[52:53], v[56:57], v[54:55]
	v_mul_f32_e32 v54, v43, v43
	v_pk_add_f32 v[52:53], v[52:53], v[52:53] op_sel:[0,1] op_sel_hi:[1,0]
	v_mov_b32_e32 v51, v0
	v_mov_b32_e32 v53, v54
	v_mul_f32_e32 v0, v35, v35
	v_mul_f32_e32 v55, v44, v44
	v_pk_add_f32 v[50:51], v[50:51], v[52:53]
	v_pk_fma_f32 v[52:53], v[34:35], v[34:35], v[0:1] op_sel_hi:[1,1,0]
	v_mul_f32_e32 v0, v37, v37
	v_mul_f32_e32 v56, v45, v45
	v_mov_b32_e32 v53, v55
	v_pk_fma_f32 v[54:55], v[36:37], v[36:37], v[0:1] op_sel_hi:[1,1,0]
	s_nop 0
	v_mov_b32_e32 v55, v56
	v_pk_add_f32 v[52:53], v[52:53], v[54:55]
	s_nop 0
	v_pk_add_f32 v[50:51], v[50:51], v[52:53]
	s_nop 0
	v_add_f32_e32 v0, v50, v51
	v_and_b32_e32 v51, 64, v242
	v_xor_b32_e32 v50, 16, v242
	v_add_u32_e32 v51, 64, v51
	v_cmp_lt_i32_e32 vcc, v50, v51
	s_nop 1
	v_cndmask_b32_e32 v50, v242, v50, vcc
	v_lshlrev_b32_e32 v50, 2, v50
	ds_bpermute_b32 v50, v50, v0
	s_waitcnt lgkmcnt(0)
	v_add_f32_e32 v0, v0, v50
	v_xor_b32_e32 v50, 32, v242
	v_cmp_lt_i32_e32 vcc, v50, v51
	s_nop 1
	v_cndmask_b32_e32 v50, v242, v50, vcc
	v_lshlrev_b32_e32 v50, 2, v50
	ds_bpermute_b32 v50, v50, v0
	s_waitcnt lgkmcnt(0)
	v_add_f32_e32 v0, v0, v50
	v_fmamk_f32 v0, v0, 0x3c800000, v241
	v_rsq_f32_e32 v0, v0
	s_nop 0
	v_pk_mul_f32 v[50:51], v[46:47], v[0:1] op_sel_hi:[1,0]
	v_pk_mul_f32 v[52:53], v[48:49], v[0:1] op_sel_hi:[1,0]
	v_mov_b64_e32 v[46:47], v[178:179]
	v_mov_b64_e32 v[48:49], v[180:181]
	v_pk_mul_f32 v[42:43], v[42:43], v[0:1] op_sel_hi:[1,0]
	v_pk_mul_f32 v[44:45], v[44:45], v[0:1] op_sel_hi:[1,0]
	v_pk_mul_f32 v[48:49], v[48:49], v[52:53]
	v_pk_mul_f32 v[46:47], v[46:47], v[50:51]
	v_pk_mul_f32 v[50:51], v[38:39], v[0:1] op_sel_hi:[1,0]
	v_pk_mul_f32 v[52:53], v[40:41], v[0:1] op_sel_hi:[1,0]
	v_mov_b64_e32 v[38:39], v[182:183]
	v_mov_b64_e32 v[40:41], v[184:185]
	v_pk_mul_f32 v[40:41], v[40:41], v[52:53]
	v_pk_mul_f32 v[38:39], v[38:39], v[50:51]
	v_pk_mul_f32 v[50:51], v[34:35], v[0:1] op_sel_hi:[1,0]
	v_pk_mul_f32 v[52:53], v[36:37], v[0:1] op_sel_hi:[1,0]
	v_mov_b64_e32 v[34:35], v[186:187]
	v_mov_b64_e32 v[36:37], v[188:189]
	v_pk_mul_f32 v[36:37], v[36:37], v[52:53]
	v_pk_mul_f32 v[34:35], v[34:35], v[50:51]
	v_mov_b64_e32 v[50:51], v[190:191]
	v_mov_b64_e32 v[52:53], v[192:193]
	v_pk_mul_f32 v[44:45], v[52:53], v[44:45]
	v_pk_mul_f32 v[42:43], v[50:51], v[42:43]

;     __device__ __forceinline__ void operator()(const f32x4 (&acc)[2][2][4][2], const Unit& u, int wr, int wc, int fr_, int fq_) const {
;     ...
;                 if (gain) {
;                     float ss = 0.f;
; #pragma unroll
;                     for (int bj = 0; bj < 2; ++bj)
; #pragma unroll
;                         for (int n = 0; n < 2; ++n) ss += (v[bj][n][0] * v[bj][n][0] + v[bj][n][1] * v[bj][n][1]) + (v[bj][n][2] * v[bj][n][2] + v[bj][n][3] * v[bj][n][3]);
;                     ss += __shfl_xor(ss, 16); ss += __shfl_xor(ss, 32);
;                     const float rinv = __builtin_amdgcn_rsqf(ss * (1.0f / 64.0f) + RMS_EPS);
; #pragma unroll
;                     for (int bj = 0; bj < 2; ++bj)
; #pragma unroll
;                         for (int n = 0; n < 2; ++n) v[bj][n] = v[bj][n] * rinv * *(const f32x4*)(gain + 32 * bj + 16 * n + 4 * fq);
;                 }
.LBB0_354:
	s_and_b64 vcc, exec, s[14:15]
	s_cbranch_vccnz .LBB0_356
	v_pk_mul_f32 v[34:35], v[32:33], v[32:33]
	v_pk_mul_f32 v[36:37], v[30:31], v[30:31]
	v_mul_f32_e32 v0, v26, v26
	v_pk_mov_b32 v[38:39], v[36:37], v[34:35] op_sel:[1,0]
	v_mov_b32_e32 v37, v35
	v_pk_add_f32 v[34:35], v[38:39], v[36:37]
	v_pk_mul_f32 v[36:37], v[24:25], v[24:25]
	v_pk_mul_f32 v[38:39], v[22:23], v[22:23]
	v_pk_add_f32 v[34:35], v[34:35], v[34:35] op_sel:[0,1] op_sel_hi:[1,0]
	v_pk_mov_b32 v[40:41], v[38:39], v[36:37] op_sel:[1,0]
	v_mov_b32_e32 v39, v37
	v_pk_add_f32 v[36:37], v[40:41], v[38:39]
	v_mul_f32_e32 v38, v27, v27
	v_pk_add_f32 v[36:37], v[36:37], v[36:37] op_sel:[0,1] op_sel_hi:[1,0]
	v_mov_b32_e32 v35, v0
	v_mov_b32_e32 v37, v38
	v_mul_f32_e32 v0, v19, v19
	v_mul_f32_e32 v39, v28, v28
	v_pk_add_f32 v[34:35], v[34:35], v[36:37]
	v_pk_fma_f32 v[36:37], v[18:19], v[18:19], v[0:1] op_sel_hi:[1,1,0]
	v_mul_f32_e32 v0, v21, v21
	v_mul_f32_e32 v40, v29, v29
	v_mov_b32_e32 v37, v39
	v_pk_fma_f32 v[38:39], v[20:21], v[20:21], v[0:1] op_sel_hi:[1,1,0]
	s_nop 0
	v_mov_b32_e32 v39, v40
	v_pk_add_f32 v[36:37], v[36:37], v[38:39]
	s_nop 0
	v_pk_add_f32 v[34:35], v[34:35], v[36:37]
	s_nop 0
	v_add_f32_e32 v0, v34, v35
	v_and_b32_e32 v35, 64, v242
	v_xor_b32_e32 v34, 16, v242
	v_add_u32_e32 v35, 64, v35
	v_cmp_lt_i32_e32 vcc, v34, v35
	s_nop 1
	v_cndmask_b32_e32 v34, v242, v34, vcc
	v_lshlrev_b32_e32 v34, 2, v34
	ds_bpermute_b32 v34, v34, v0
	s_waitcnt lgkmcnt(0)
	v_add_f32_e32 v0, v0, v34
	v_xor_b32_e32 v34, 32, v242
	v_cmp_lt_i32_e32 vcc, v34, v35
	s_nop 1
	v_cndmask_b32_e32 v34, v242, v34, vcc
	v_lshlrev_b32_e32 v34, 2, v34
	ds_bpermute_b32 v34, v34, v0
	s_waitcnt lgkmcnt(0)
	v_add_f32_e32 v0, v0, v34
	v_fmamk_f32 v0, v0, 0x3c800000, v241
	v_rsq_f32_e32 v0, v0
	s_nop 0
	v_pk_mul_f32 v[34:35], v[30:31], v[0:1] op_sel_hi:[1,0]
	v_pk_mul_f32 v[36:37], v[32:33], v[0:1] op_sel_hi:[1,0]
	v_mov_b64_e32 v[30:31], v[178:179]
	v_mov_b64_e32 v[32:33], v[180:181]
	v_pk_mul_f32 v[26:27], v[26:27], v[0:1] op_sel_hi:[1,0]
	v_pk_mul_f32 v[28:29], v[28:29], v[0:1] op_sel_hi:[1,0]
	v_pk_mul_f32 v[32:33], v[32:33], v[36:37]
	v_pk_mul_f32 v[30:31], v[30:31], v[34:35]
	v_pk_mul_f32 v[34:35], v[22:23], v[0:1] op_sel_hi:[1,0]
	v_pk_mul_f32 v[36:37], v[24:25], v[0:1] op_sel_hi:[1,0]
	v_mov_b64_e32 v[22:23], v[182:183]
	v_mov_b64_e32 v[24:25], v[184:185]
	v_pk_mul_f32 v[24:25], v[24:25], v[36:37]
	v_pk_mul_f32 v[22:23], v[22:23], v[34:35]
	v_pk_mul_f32 v[34:35], v[18:19], v[0:1] op_sel_hi:[1,0]
	v_pk_mul_f32 v[36:37], v[20:21], v[0:1] op_sel_hi:[1,0]
	v_mov_b64_e32 v[18:19], v[186:187]
	v_mov_b64_e32 v[20:21], v[188:189]
	v_pk_mul_f32 v[20:21], v[20:21], v[36:37]
	v_pk_mul_f32 v[18:19], v[18:19], v[34:35]
	v_mov_b64_e32 v[34:35], v[190:191]
	v_mov_b64_e32 v[36:37], v[192:193]
	v_pk_mul_f32 v[28:29], v[36:37], v[28:29]
	v_pk_mul_f32 v[26:27], v[34:35], v[26:27]

;     __device__ __forceinline__ void operator()(const f32x4 (&acc)[2][2][4][2], const Unit& u, int wr, int wc, int fr_, int fq_) const {
;     ...
;                 if (gain) {
;                     float ss = 0.f;
; #pragma unroll
;                     for (int bj = 0; bj < 2; ++bj)
; #pragma unroll
;                         for (int n = 0; n < 2; ++n) ss += (v[bj][n][0] * v[bj][n][0] + v[bj][n][1] * v[bj][n][1]) + (v[bj][n][2] * v[bj][n][2] + v[bj][n][3] * v[bj][n][3]);
;                     ss += __shfl_xor(ss, 16); ss += __shfl_xor(ss, 32);
;                     const float rinv = __builtin_amdgcn_rsqf(ss * (1.0f / 64.0f) + RMS_EPS);
; #pragma unroll
;                     for (int bj = 0; bj < 2; ++bj)
; #pragma unroll
;                         for (int n = 0; n < 2; ++n) v[bj][n] = v[bj][n] * rinv * *(const f32x4*)(gain + 32 * bj + 16 * n + 4 * fq);
;                 }
.LBB0_378:
	s_and_b64 vcc, exec, s[14:15]
	s_cbranch_vccnz .LBB0_380
	v_pk_mul_f32 v[18:19], v[16:17], v[16:17]
	v_pk_mul_f32 v[20:21], v[14:15], v[14:15]
	v_mul_f32_e32 v0, v10, v10
	v_pk_mov_b32 v[22:23], v[20:21], v[18:19] op_sel:[1,0]
	v_mov_b32_e32 v21, v19
	v_pk_add_f32 v[18:19], v[22:23], v[20:21]
	v_pk_mul_f32 v[20:21], v[8:9], v[8:9]
	v_pk_mul_f32 v[22:23], v[6:7], v[6:7]
	v_pk_add_f32 v[18:19], v[18:19], v[18:19] op_sel:[0,1] op_sel_hi:[1,0]
	v_pk_mov_b32 v[24:25], v[22:23], v[20:21] op_sel:[1,0]
	v_mov_b32_e32 v23, v21
	v_pk_add_f32 v[20:21], v[24:25], v[22:23]
	v_mul_f32_e32 v22, v11, v11
	v_pk_add_f32 v[20:21], v[20:21], v[20:21] op_sel:[0,1] op_sel_hi:[1,0]
	v_mov_b32_e32 v19, v0
	v_mov_b32_e32 v21, v22
	v_mul_f32_e32 v0, v3, v3
	v_mul_f32_e32 v23, v12, v12
	v_pk_add_f32 v[18:19], v[18:19], v[20:21]
	v_pk_fma_f32 v[20:21], v[2:3], v[2:3], v[0:1] op_sel_hi:[1,1,0]
	v_mul_f32_e32 v0, v5, v5
	v_mul_f32_e32 v24, v13, v13
	v_mov_b32_e32 v21, v23
	v_pk_fma_f32 v[22:23], v[4:5], v[4:5], v[0:1] op_sel_hi:[1,1,0]
	s_nop 0
	v_mov_b32_e32 v23, v24
	v_pk_add_f32 v[20:21], v[20:21], v[22:23]
	s_nop 0
	v_pk_add_f32 v[18:19], v[18:19], v[20:21]
	s_nop 0
	v_add_f32_e32 v0, v18, v19
	v_and_b32_e32 v19, 64, v242
	v_xor_b32_e32 v18, 16, v242
	v_add_u32_e32 v19, 64, v19
	v_cmp_lt_i32_e32 vcc, v18, v19
	s_nop 1
	v_cndmask_b32_e32 v18, v242, v18, vcc
	v_lshlrev_b32_e32 v18, 2, v18
	ds_bpermute_b32 v18, v18, v0
	s_waitcnt lgkmcnt(0)
	v_add_f32_e32 v0, v0, v18
	v_xor_b32_e32 v18, 32, v242
	v_cmp_lt_i32_e32 vcc, v18, v19
	s_nop 1
	v_cndmask_b32_e32 v18, v242, v18, vcc
	v_lshlrev_b32_e32 v18, 2, v18
	ds_bpermute_b32 v18, v18, v0
	s_waitcnt lgkmcnt(0)
	v_add_f32_e32 v0, v0, v18
	v_fmamk_f32 v0, v0, 0x3c800000, v241
	v_rsq_f32_e32 v0, v0
	s_nop 0
	v_pk_mul_f32 v[18:19], v[14:15], v[0:1] op_sel_hi:[1,0]
	v_pk_mul_f32 v[20:21], v[16:17], v[0:1] op_sel_hi:[1,0]
	v_mov_b64_e32 v[14:15], v[178:179]
	v_mov_b64_e32 v[16:17], v[180:181]
	v_pk_mul_f32 v[10:11], v[10:11], v[0:1] op_sel_hi:[1,0]
	v_pk_mul_f32 v[12:13], v[12:13], v[0:1] op_sel_hi:[1,0]
	v_pk_mul_f32 v[16:17], v[16:17], v[20:21]
	v_pk_mul_f32 v[14:15], v[14:15], v[18:19]
	v_pk_mul_f32 v[18:19], v[6:7], v[0:1] op_sel_hi:[1,0]
	v_pk_mul_f32 v[20:21], v[8:9], v[0:1] op_sel_hi:[1,0]
	v_mov_b64_e32 v[6:7], v[182:183]
	v_mov_b64_e32 v[8:9], v[184:185]
	v_pk_mul_f32 v[8:9], v[8:9], v[20:21]
	v_pk_mul_f32 v[6:7], v[6:7], v[18:19]
	v_pk_mul_f32 v[18:19], v[2:3], v[0:1] op_sel_hi:[1,0]
	v_pk_mul_f32 v[20:21], v[4:5], v[0:1] op_sel_hi:[1,0]
	v_mov_b64_e32 v[2:3], v[186:187]
	v_mov_b64_e32 v[4:5], v[188:189]
	v_pk_mul_f32 v[4:5], v[4:5], v[20:21]
	v_pk_mul_f32 v[2:3], v[2:3], v[18:19]
	v_mov_b64_e32 v[18:19], v[190:191]
	v_mov_b64_e32 v[20:21], v[192:193]
	v_pk_mul_f32 v[12:13], v[20:21], v[12:13]
	v_pk_mul_f32 v[10:11], v[18:19], v[10:11]
